# attention tile loop: first map-0 PV MFMA of each sub-tile issued right after its packed operand is converted (before the late V reads, row-sum update and first exponentials)
# speedup vs baseline: 1.0076x; 1.0076x over previous
; #define LAS __attribute__((address_space(3)))
; __device__ __forceinline__ void dattn_unit(LAS unsigned char* lds, int b, int h, int qb, const bf16* Q, const bf16* K, const bf16* V, bf16* YB, float lam, const float* subg, float oml, int tid) {
;     ...
;             for (int cb = 0; cb < 4; ++cb) { const LAS bf16* vp = Vt + (32 * cb + ql) * 72 + 32 * sub + 4 * hi;
;                 const v2u a0 = *(const LAS v2u*)(vp), a1 = *(const LAS v2u*)(vp + 8), a2 = *(const LAS v2u*)(vp + 16), a3 = *(const LAS v2u*)(vp + 24);
;                 const v4u f0 = {a0.x, a0.y, a1.x, a1.y}, f1 = {a2.x, a2.y, a3.x, a3.y};
;                 o[0][cb] = __builtin_amdgcn_mfma_f32_32x32x16_bf16(__builtin_bit_cast(bf16x8, f0), pA0, o[0][cb], 0, 0, 0);
;                 o[1][cb] = __builtin_amdgcn_mfma_f32_32x32x16_bf16(__builtin_bit_cast(bf16x8, f0), pA1, o[1][cb], 0, 0, 0);
;                 o[0][cb] = __builtin_amdgcn_mfma_f32_32x32x16_bf16(__builtin_bit_cast(bf16x8, f1), pB0, o[0][cb], 0, 0, 0);
;                 o[1][cb] = __builtin_amdgcn_mfma_f32_32x32x16_bf16(__builtin_bit_cast(bf16x8, f1), pB1, o[1][cb], 0, 0, 0); }
.LBB0_232:
	v_cvt_pk_bf16_f32 v224, v201, v202
	v_cvt_pk_bf16_f32 v225, v203, v204
	v_cvt_pk_bf16_f32 v226, v205, v206
	v_cvt_pk_bf16_f32 v227, v207, v218
	ds_read_b128 v[204:207], v219 offset:18464
	ds_read_b128 v[200:203], v219 offset:32288
	v_cvt_pk_bf16_f32 v148, v147, v148
	v_cvt_pk_bf16_f32 v149, v149, v150
	s_waitcnt lgkmcnt(2)
	v_mfma_f32_32x32x16_bf16 v[80:95], v[228:231], v[224:227], v[80:95]
	v_cvt_pk_bf16_f32 v150, v151, v152
	v_cvt_pk_bf16_f32 v151, v153, v154
	v_add_f32_e32 v179, v179, v145
	v_exp_f32_e32 v155, v128
	v_exp_f32_e32 v129, v129
	v_exp_f32_e32 v130, v130
	v_exp_f32_e32 v131, v131
	v_exp_f32_e32 v132, v132
	v_add_f32_e32 v128, v129, v155
	v_exp_f32_e32 v156, v133
	v_mfma_f32_32x32x16_bf16 v[80:95], v[232:235], v[148:151], v[80:95]
	v_add_f32_e32 v128, v130, v128
	v_exp_f32_e32 v157, v134
	v_add_f32_e32 v128, v131, v128
	v_exp_f32_e32 v158, v135
	v_mfma_f32_32x32x16_bf16 v[48:63], v[236:239], v[224:227], v[48:63]
	v_add_f32_e32 v128, v132, v128
	v_exp_f32_e32 v133, v136
	v_add_f32_e32 v128, v156, v128
	v_exp_f32_e32 v134, v137
	v_mfma_f32_32x32x16_bf16 v[48:63], v[240:243], v[148:151], v[48:63]
	v_add_f32_e32 v128, v157, v128
	v_exp_f32_e32 v135, v138
	v_add_f32_e32 v128, v158, v128
	v_exp_f32_e32 v136, v139
	v_mfma_f32_32x32x16_bf16 v[16:31], v[212:215], v[224:227], v[16:31]
	v_add_f32_e32 v128, v133, v128
	v_exp_f32_e32 v137, v140
	v_add_f32_e32 v128, v134, v128
	v_exp_f32_e32 v138, v141
	v_mfma_f32_32x32x16_bf16 v[112:127], v[220:223], v[224:227], v[112:127]
	v_add_f32_e32 v128, v135, v128
	v_exp_f32_e32 v139, v142
	v_add_f32_e32 v128, v136, v128
	v_exp_f32_e32 v140, v143
	s_waitcnt lgkmcnt(1)
	v_mfma_f32_32x32x16_bf16 v[112:127], v[204:207], v[148:151], v[112:127]
	v_add_f32_e32 v128, v137, v128
	v_add_f32_e32 v128, v138, v128
	v_add_f32_e32 v128, v139, v128
	v_add_f32_e32 v128, v140, v128
	s_waitcnt lgkmcnt(0)
	v_mfma_f32_32x32x16_bf16 v[16:31], v[200:203], v[148:151], v[16:31]
	v_cmp_lt_f32_e32 vcc, s82, v128
	s_cmp_lg_u64 vcc, 0
	s_cselect_b64 s[46:47], -1, 0
	s_cbranch_vccz .LBB0_234
	v_max_f32_e32 v141, v131, v131
	v_max_f32_e32 v142, v130, v130
	v_max_f32_e32 v141, v142, v141
	v_max_f32_e32 v142, v158, v158
	v_max_f32_e32 v143, v157, v157
	v_max_f32_e32 v142, v143, v142
	v_max_f32_e32 v143, v134, v134
	v_max_f32_e32 v144, v133, v133
	v_max_f32_e32 v143, v144, v143
	v_max_f32_e32 v144, v136, v136
	v_max_f32_e32 v159, v135, v135
	v_max_f32_e32 v144, v159, v144
	v_max_f32_e32 v159, v140, v140
	v_max_f32_e32 v147, v139, v139
	v_max_f32_e32 v159, v147, v159
	v_max3_f32 v159, v137, v138, v159
	v_max3_f32 v141, v155, v129, v141
	v_max3_f32 v142, v132, v156, v142
	v_max3_f32 v143, v143, v144, v159
	v_max3_f32 v141, v141, v142, v143
	v_mov_b32_e32 v142, v141
	s_nop 1
	v_permlane32_swap_b32_e32 v141, v142
	v_max_f32_e32 v142, v142, v142
	v_max_f32_e32 v141, v141, v141
	v_max_f32_e32 v144, v141, v142

; #define LAS __attribute__((address_space(3)))
; __device__ __forceinline__ void dattn_unit(LAS unsigned char* lds, int b, int h, int qb, const bf16* Q, const bf16* K, const bf16* V, bf16* YB, float lam, const float* subg, float oml, int tid) {
;     ...
;             for (int cb = 0; cb < 4; ++cb) { const LAS bf16* vp = Vt + (32 * cb + ql) * 72 + 32 * sub + 4 * hi;
;                 const v2u a0 = *(const LAS v2u*)(vp), a1 = *(const LAS v2u*)(vp + 8), a2 = *(const LAS v2u*)(vp + 16), a3 = *(const LAS v2u*)(vp + 24);
;                 const v4u f0 = {a0.x, a0.y, a1.x, a1.y}, f1 = {a2.x, a2.y, a3.x, a3.y};
;                 o[0][cb] = __builtin_amdgcn_mfma_f32_32x32x16_bf16(__builtin_bit_cast(bf16x8, f0), pA0, o[0][cb], 0, 0, 0);
;                 o[1][cb] = __builtin_amdgcn_mfma_f32_32x32x16_bf16(__builtin_bit_cast(bf16x8, f0), pA1, o[1][cb], 0, 0, 0);
;                 o[0][cb] = __builtin_amdgcn_mfma_f32_32x32x16_bf16(__builtin_bit_cast(bf16x8, f1), pB0, o[0][cb], 0, 0, 0);
;                 o[1][cb] = __builtin_amdgcn_mfma_f32_32x32x16_bf16(__builtin_bit_cast(bf16x8, f1), pB1, o[1][cb], 0, 0, 0); }
.LBB0_243:
	v_cvt_pk_bf16_f32 v205, v205, v206
	v_cvt_pk_bf16_f32 v206, v207, v218
	v_cvt_pk_bf16_f32 v207, v219, v220
	v_cvt_pk_bf16_f32 v204, v199, v204
	ds_read_b128 v[218:221], v243 offset:32352
	v_cvt_pk_bf16_f32 v148, v147, v148
	v_cvt_pk_bf16_f32 v149, v149, v150
	s_waitcnt lgkmcnt(1)
	v_mfma_f32_32x32x16_bf16 v[80:95], v[222:225], v[204:207], v[80:95]
	v_cvt_pk_bf16_f32 v150, v151, v152
	v_cvt_pk_bf16_f32 v151, v153, v154
	v_add_f32_e32 v179, v179, v145
	v_exp_f32_e32 v155, v128
	v_exp_f32_e32 v129, v129
	v_exp_f32_e32 v130, v130
	v_exp_f32_e32 v131, v131
	v_exp_f32_e32 v132, v132
	v_add_f32_e32 v128, v129, v155
	v_exp_f32_e32 v156, v133
	v_mfma_f32_32x32x16_bf16 v[80:95], v[226:229], v[148:151], v[80:95]
	v_add_f32_e32 v128, v130, v128
	v_exp_f32_e32 v157, v134
	v_add_f32_e32 v128, v131, v128
	v_exp_f32_e32 v158, v135
	v_mfma_f32_32x32x16_bf16 v[48:63], v[230:233], v[204:207], v[48:63]
	v_add_f32_e32 v128, v132, v128
	v_exp_f32_e32 v133, v136
	v_add_f32_e32 v128, v156, v128
	v_exp_f32_e32 v134, v137
	v_mfma_f32_32x32x16_bf16 v[48:63], v[234:237], v[148:151], v[48:63]
	v_add_f32_e32 v128, v157, v128
	v_exp_f32_e32 v135, v138
	v_add_f32_e32 v128, v158, v128
	v_exp_f32_e32 v136, v139
	v_mfma_f32_32x32x16_bf16 v[16:31], v[238:241], v[204:207], v[16:31]
	v_add_f32_e32 v128, v133, v128
	v_exp_f32_e32 v137, v140
	v_add_f32_e32 v128, v134, v128
	v_exp_f32_e32 v138, v141
	v_mfma_f32_32x32x16_bf16 v[112:127], v[212:215], v[204:207], v[112:127]
	v_add_f32_e32 v128, v135, v128
	v_exp_f32_e32 v139, v142
	v_add_f32_e32 v128, v136, v128
	v_exp_f32_e32 v140, v143
	v_mfma_f32_32x32x16_bf16 v[112:127], v[200:203], v[148:151], v[112:127]
	v_add_f32_e32 v128, v137, v128
	v_add_f32_e32 v128, v138, v128
	v_add_f32_e32 v128, v139, v128
	v_add_f32_e32 v128, v140, v128
	s_waitcnt lgkmcnt(0)
	v_mfma_f32_32x32x16_bf16 v[16:31], v[218:221], v[148:151], v[16:31]
	v_cmp_lt_f32_e32 vcc, s82, v128
	s_cmp_lg_u64 vcc, 0
	s_cselect_b64 s[46:47], -1, 0
	s_cbranch_vccz .LBB0_245
	v_max_f32_e32 v141, v131, v131
	v_max_f32_e32 v142, v130, v130
	v_max_f32_e32 v141, v142, v141
	v_max_f32_e32 v142, v158, v158
	v_max_f32_e32 v143, v157, v157
	v_max_f32_e32 v142, v143, v142
	v_max_f32_e32 v143, v134, v134
	v_max_f32_e32 v144, v133, v133
	v_max_f32_e32 v143, v144, v143
	v_max_f32_e32 v144, v136, v136
	v_max_f32_e32 v159, v135, v135
	v_max_f32_e32 v144, v159, v144
	v_max_f32_e32 v159, v140, v140
	v_max_f32_e32 v147, v139, v139
	v_max_f32_e32 v159, v147, v159
	v_max3_f32 v159, v137, v138, v159
	v_max3_f32 v141, v155, v129, v141
	v_max3_f32 v142, v132, v156, v142
	v_max3_f32 v143, v143, v144, v159
	v_max3_f32 v141, v141, v142, v143
	v_mov_b32_e32 v142, v141
	s_nop 1
	v_permlane32_swap_b32_e32 v141, v142
	v_max_f32_e32 v142, v142, v142
	v_max_f32_e32 v141, v141, v141
	v_max_f32_e32 v144, v141, v142
